# P2: peeled first K-iter of non-first units (vmcnt 16 in phases 1-2, acc init via srcC=0), rstd wait vmcnt(8)
# speedup vs baseline: 1.0087x; 1.0087x over previous
.LBB0_595:
	s_ashr_i32 s91, s90, 31
	s_lshl_b64 s[42:43], s[90:91], 19
	s_add_u32 s68, s8, s42
	s_addc_u32 s69, s9, s43
	s_and_b64 s[42:43], s[38:39], exec
	s_cselect_b32 s57, s69, s45
	s_cselect_b32 s91, s68, s44
	s_ashr_i32 s1, s0, 31
	s_lshl_b64 s[42:43], s[0:1], 19
	s_add_u32 s88, s94, s42
	s_addc_u32 s89, s71, s43
	s_and_b64 s[42:43], s[38:39], exec
	s_cselect_b32 s1, s89, s77
	s_cselect_b32 s53, s88, s76
	s_add_u32 s44, s44, 0x40080
	s_addc_u32 s45, s45, 0
	s_add_u32 s64, s76, 0x100
	s_addc_u32 s65, s77, 0
	s_mov_b32 s42, -2
	s_cmp_lg_u32 s51, 1
	s_cbranch_scc0 .Lp2_zero
	v_add_u32_e32 v178, s95, v165
	v_add_u32_e32 v200, s86, v165
	ds_read_b128 v[156:159], v178
	ds_read_b128 v[170:173], v178 offset:1024
	ds_read_b128 v[174:177], v178 offset:2048
	ds_read_b128 v[178:181], v178 offset:3072
	ds_read_b128 v[182:185], v200
	ds_read_b128 v[186:189], v200 offset:1024
	ds_read_b128 v[190:193], v200 offset:2048
	ds_read_b128 v[204:207], v200 offset:3072
	s_add_u32 s43, s44, 0xfffc0080
	s_addc_u32 s72, s45, -1
	s_cmp_eq_u32 s42, 12
	s_cselect_b32 s77, s57, s72
	s_cselect_b32 s76, s91, s43
	s_cselect_b32 vcc_hi, s1, s65
	s_cselect_b32 vcc_lo, s53, s64
	v_lshl_add_u64 v[232:233], s[44:45], 0, v[152:153]
	s_add_i32 m0, s48, 0xc000
	ds_read_b128 v[208:211], v169
	ds_read_b128 v[212:215], v169 offset:1024
	ds_read_b128 v[216:219], v169 offset:2048
	ds_read_b128 v[220:223], v169 offset:3072
	ds_read_b128 v[224:227], v169 offset:4096
	ds_read_b128 v[228:231], v169 offset:5120
	ds_read_b128 v[238:241], v169 offset:6144
	ds_read_b128 v[242:245], v169 offset:7168
	global_load_lds_dwordx4 v[232:233], off
	v_lshl_add_u64 v[232:233], s[44:45], 0, v[154:155]
	s_add_i32 m0, s48, 0xe000
	s_nop 0
	global_load_lds_dwordx4 v[232:233], off
	s_waitcnt vmcnt(16)
	s_waitcnt lgkmcnt(0)
	s_barrier
	s_setprio 1
	s_waitcnt lgkmcnt(0)
	v_mfma_f32_16x16x32_bf16 v[142:145], v[156:159], v[208:211], 0
	v_mfma_f32_16x16x32_bf16 v[138:141], v[174:177], v[208:211], 0
	v_mfma_f32_16x16x32_bf16 v[126:129], v[156:159], v[216:219], 0
	v_mfma_f32_16x16x32_bf16 v[122:125], v[174:177], v[216:219], 0
	v_mfma_f32_16x16x32_bf16 v[110:113], v[156:159], v[224:227], 0
	v_mfma_f32_16x16x32_bf16 v[106:109], v[174:177], v[224:227], 0
	v_mfma_f32_16x16x32_bf16 v[94:97], v[156:159], v[238:241], 0
	v_mfma_f32_16x16x32_bf16 v[90:93], v[174:177], v[238:241], 0
	v_mfma_f32_16x16x32_bf16 v[142:145], v[170:173], v[212:215], v[142:145]
	v_mfma_f32_16x16x32_bf16 v[138:141], v[178:181], v[212:215], v[138:141]
	v_mfma_f32_16x16x32_bf16 v[126:129], v[170:173], v[220:223], v[126:129]
	v_mfma_f32_16x16x32_bf16 v[122:125], v[178:181], v[220:223], v[122:125]
	v_mfma_f32_16x16x32_bf16 v[110:113], v[170:173], v[228:231], v[110:113]
	v_mfma_f32_16x16x32_bf16 v[106:109], v[178:181], v[228:231], v[106:109]
	v_mfma_f32_16x16x32_bf16 v[94:97], v[170:173], v[242:245], v[94:97]
	v_mfma_f32_16x16x32_bf16 v[90:93], v[178:181], v[242:245], v[90:93]
	s_setprio 0
	s_setprio 1
	v_mfma_f32_16x16x32_bf16 v[134:137], v[182:185], v[208:211], 0
	v_mfma_f32_16x16x32_bf16 v[130:133], v[190:193], v[208:211], 0
	v_mfma_f32_16x16x32_bf16 v[118:121], v[182:185], v[216:219], 0
	v_mfma_f32_16x16x32_bf16 v[114:117], v[190:193], v[216:219], 0
	v_mfma_f32_16x16x32_bf16 v[102:105], v[182:185], v[224:227], 0
	v_mfma_f32_16x16x32_bf16 v[98:101], v[190:193], v[224:227], 0
	v_mfma_f32_16x16x32_bf16 v[86:89], v[182:185], v[238:241], 0
	v_mfma_f32_16x16x32_bf16 v[82:85], v[190:193], v[238:241], 0
	v_mfma_f32_16x16x32_bf16 v[134:137], v[186:189], v[212:215], v[134:137]
	v_mfma_f32_16x16x32_bf16 v[130:133], v[204:207], v[212:215], v[130:133]
	v_mfma_f32_16x16x32_bf16 v[118:121], v[186:189], v[220:223], v[118:121]
	v_mfma_f32_16x16x32_bf16 v[114:117], v[204:207], v[220:223], v[114:117]
	v_mfma_f32_16x16x32_bf16 v[102:105], v[186:189], v[228:231], v[102:105]
	v_mfma_f32_16x16x32_bf16 v[98:101], v[204:207], v[228:231], v[98:101]
	v_mfma_f32_16x16x32_bf16 v[86:89], v[186:189], v[242:245], v[86:89]
	v_mfma_f32_16x16x32_bf16 v[82:85], v[204:207], v[242:245], v[82:85]
	s_setprio 0
	s_barrier
	s_mov_b32 m0, s55
	v_lshl_add_u64 v[232:233], vcc, 0, v[0:1]
	s_add_u32 s72, vcc_lo, 0x40000
	ds_read_b128 v[208:211], v169 offset:16384
	ds_read_b128 v[212:215], v169 offset:17408
	ds_read_b128 v[216:219], v169 offset:18432
	ds_read_b128 v[220:223], v169 offset:19456
	ds_read_b128 v[224:227], v169 offset:20480
	ds_read_b128 v[228:231], v169 offset:21504
	ds_read_b128 v[238:241], v169 offset:22528
	ds_read_b128 v[242:245], v169 offset:23552
	global_load_lds_dwordx4 v[232:233], off
	v_lshl_add_u64 v[246:247], vcc, 0, v[150:151]
	s_mov_b32 m0, s85
	s_addc_u32 s73, vcc_hi, 0
	global_load_lds_dwordx4 v[246:247], off
	v_lshl_add_u64 v[248:249], s[72:73], 0, v[0:1]
	s_mov_b32 m0, s58
	v_lshl_add_u64 v[250:251], s[76:77], 0, v[148:149]
	global_load_lds_dwordx4 v[248:249], off
	v_lshl_add_u64 v[248:249], s[72:73], 0, v[150:151]
	s_mov_b32 m0, s97
	s_nop 0
	global_load_lds_dwordx4 v[248:249], off
	v_lshl_add_u64 v[248:249], s[76:77], 0, v[146:147]
	s_mov_b32 m0, s48
	s_nop 0
	global_load_lds_dwordx4 v[248:249], off
	s_mov_b32 m0, s59
	s_nop 0
	global_load_lds_dwordx4 v[250:251], off
	s_waitcnt vmcnt(16)
	s_waitcnt lgkmcnt(0)
	s_barrier
	s_setprio 1
	s_waitcnt lgkmcnt(0)
	v_mfma_f32_16x16x32_bf16 v[78:81], v[156:159], v[208:211], 0
	v_mfma_f32_16x16x32_bf16 v[74:77], v[174:177], v[208:211], 0
	v_mfma_f32_16x16x32_bf16 v[66:69], v[156:159], v[216:219], 0
	v_mfma_f32_16x16x32_bf16 v[58:61], v[174:177], v[216:219], 0
	v_mfma_f32_16x16x32_bf16 v[46:49], v[156:159], v[224:227], 0
	v_mfma_f32_16x16x32_bf16 v[42:45], v[174:177], v[224:227], 0
	v_mfma_f32_16x16x32_bf16 v[30:33], v[156:159], v[238:241], 0
	v_mfma_f32_16x16x32_bf16 v[26:29], v[174:177], v[238:241], 0
	v_mfma_f32_16x16x32_bf16 v[78:81], v[170:173], v[212:215], v[78:81]
	v_mfma_f32_16x16x32_bf16 v[74:77], v[178:181], v[212:215], v[74:77]
	v_mfma_f32_16x16x32_bf16 v[66:69], v[170:173], v[220:223], v[66:69]
	v_mfma_f32_16x16x32_bf16 v[58:61], v[178:181], v[220:223], v[58:61]
	v_mfma_f32_16x16x32_bf16 v[46:49], v[170:173], v[228:231], v[46:49]
	v_mfma_f32_16x16x32_bf16 v[42:45], v[178:181], v[228:231], v[42:45]
	v_mfma_f32_16x16x32_bf16 v[30:33], v[170:173], v[242:245], v[30:33]
	v_mfma_f32_16x16x32_bf16 v[26:29], v[178:181], v[242:245], v[26:29]
	s_setprio 0
	s_setprio 1
	v_mfma_f32_16x16x32_bf16 v[70:73], v[182:185], v[208:211], 0
	v_mfma_f32_16x16x32_bf16 v[62:65], v[190:193], v[208:211], 0
	v_mfma_f32_16x16x32_bf16 v[54:57], v[182:185], v[216:219], 0
	v_mfma_f32_16x16x32_bf16 v[50:53], v[190:193], v[216:219], 0
	v_mfma_f32_16x16x32_bf16 v[38:41], v[182:185], v[224:227], 0
	v_mfma_f32_16x16x32_bf16 v[34:37], v[190:193], v[224:227], 0
	v_mfma_f32_16x16x32_bf16 v[22:25], v[182:185], v[238:241], 0
	v_mfma_f32_16x16x32_bf16 v[18:21], v[190:193], v[238:241], 0
	v_mfma_f32_16x16x32_bf16 v[70:73], v[186:189], v[212:215], v[70:73]
	v_mfma_f32_16x16x32_bf16 v[62:65], v[204:207], v[212:215], v[62:65]
	v_mfma_f32_16x16x32_bf16 v[54:57], v[186:189], v[220:223], v[54:57]
	v_mfma_f32_16x16x32_bf16 v[50:53], v[204:207], v[220:223], v[50:53]
	v_mfma_f32_16x16x32_bf16 v[38:41], v[186:189], v[228:231], v[38:41]
	v_mfma_f32_16x16x32_bf16 v[34:37], v[204:207], v[228:231], v[34:37]
	v_mfma_f32_16x16x32_bf16 v[22:25], v[186:189], v[242:245], v[22:25]
	v_mfma_f32_16x16x32_bf16 v[18:21], v[204:207], v[242:245], v[18:21]
	s_setprio 0
	s_barrier
	v_add_u32_e32 v178, s87, v165
	v_add_u32_e32 v200, s92, v165
	ds_read_b128 v[156:159], v178
	ds_read_b128 v[170:173], v178 offset:1024
	ds_read_b128 v[174:177], v178 offset:2048
	ds_read_b128 v[178:181], v178 offset:3072
	ds_read_b128 v[182:185], v200
	ds_read_b128 v[186:189], v200 offset:1024
	ds_read_b128 v[190:193], v200 offset:2048
	ds_read_b128 v[204:207], v200 offset:3072
	s_add_u32 s72, s76, 0x40000
	s_addc_u32 s73, s77, 0
	s_mov_b32 m0, s82
	v_lshl_add_u64 v[200:201], s[72:73], 0, v[146:147]
	ds_read_b128 v[208:211], v169 offset:32768
	ds_read_b128 v[212:215], v169 offset:33792
	ds_read_b128 v[216:219], v169 offset:34816
	ds_read_b128 v[220:223], v169 offset:35840
	ds_read_b128 v[224:227], v169 offset:36864
	ds_read_b128 v[228:231], v169 offset:37888
	ds_read_b128 v[238:241], v169 offset:38912
	ds_read_b128 v[242:245], v169 offset:39936
	global_load_lds_dwordx4 v[200:201], off
	v_lshl_add_u64 v[200:201], s[72:73], 0, v[148:149]
	s_mov_b32 m0, s50
	s_nop 0
	global_load_lds_dwordx4 v[200:201], off
	s_waitcnt vmcnt(8)
	s_waitcnt lgkmcnt(0)
	s_barrier
	s_setprio 1
	s_waitcnt lgkmcnt(0)
	v_mfma_f32_16x16x32_bf16 v[142:145], v[156:159], v[208:211], v[142:145]
	v_mfma_f32_16x16x32_bf16 v[138:141], v[174:177], v[208:211], v[138:141]
	v_mfma_f32_16x16x32_bf16 v[126:129], v[156:159], v[216:219], v[126:129]
	v_mfma_f32_16x16x32_bf16 v[122:125], v[174:177], v[216:219], v[122:125]
	v_mfma_f32_16x16x32_bf16 v[110:113], v[156:159], v[224:227], v[110:113]
	v_mfma_f32_16x16x32_bf16 v[106:109], v[174:177], v[224:227], v[106:109]
	v_mfma_f32_16x16x32_bf16 v[94:97], v[156:159], v[238:241], v[94:97]
	v_mfma_f32_16x16x32_bf16 v[90:93], v[174:177], v[238:241], v[90:93]
	v_mfma_f32_16x16x32_bf16 v[142:145], v[170:173], v[212:215], v[142:145]
	v_mfma_f32_16x16x32_bf16 v[138:141], v[178:181], v[212:215], v[138:141]
	v_mfma_f32_16x16x32_bf16 v[126:129], v[170:173], v[220:223], v[126:129]
	v_mfma_f32_16x16x32_bf16 v[122:125], v[178:181], v[220:223], v[122:125]
	v_mfma_f32_16x16x32_bf16 v[110:113], v[170:173], v[228:231], v[110:113]
	v_mfma_f32_16x16x32_bf16 v[106:109], v[178:181], v[228:231], v[106:109]
	v_mfma_f32_16x16x32_bf16 v[94:97], v[170:173], v[242:245], v[94:97]
	v_mfma_f32_16x16x32_bf16 v[90:93], v[178:181], v[242:245], v[90:93]
	s_setprio 0
	s_setprio 1
	v_mfma_f32_16x16x32_bf16 v[134:137], v[182:185], v[208:211], v[134:137]
	v_mfma_f32_16x16x32_bf16 v[130:133], v[190:193], v[208:211], v[130:133]
	v_mfma_f32_16x16x32_bf16 v[118:121], v[182:185], v[216:219], v[118:121]
	v_mfma_f32_16x16x32_bf16 v[114:117], v[190:193], v[216:219], v[114:117]
	v_mfma_f32_16x16x32_bf16 v[102:105], v[182:185], v[224:227], v[102:105]
	v_mfma_f32_16x16x32_bf16 v[98:101], v[190:193], v[224:227], v[98:101]
	v_mfma_f32_16x16x32_bf16 v[86:89], v[182:185], v[238:241], v[86:89]
	v_mfma_f32_16x16x32_bf16 v[82:85], v[190:193], v[238:241], v[82:85]
	v_mfma_f32_16x16x32_bf16 v[134:137], v[186:189], v[212:215], v[134:137]
	v_mfma_f32_16x16x32_bf16 v[130:133], v[204:207], v[212:215], v[130:133]
	v_mfma_f32_16x16x32_bf16 v[118:121], v[186:189], v[220:223], v[118:121]
	v_mfma_f32_16x16x32_bf16 v[114:117], v[204:207], v[220:223], v[114:117]
	v_mfma_f32_16x16x32_bf16 v[102:105], v[186:189], v[228:231], v[102:105]
	v_mfma_f32_16x16x32_bf16 v[98:101], v[204:207], v[228:231], v[98:101]
	v_mfma_f32_16x16x32_bf16 v[86:89], v[186:189], v[242:245], v[86:89]
	v_mfma_f32_16x16x32_bf16 v[82:85], v[204:207], v[242:245], v[82:85]
	s_setprio 0
	s_barrier
	s_mov_b32 m0, s60
	v_lshl_add_u64 v[200:201], v[232:233], 0, s[80:81]
	s_add_u32 s72, vcc_lo, 0x40080
	ds_read_b128 v[208:211], v169 offset:49152
	ds_read_b128 v[212:215], v169 offset:50176
	ds_read_b128 v[216:219], v169 offset:51200
	ds_read_b128 v[220:223], v169 offset:52224
	ds_read_b128 v[224:227], v169 offset:53248
	ds_read_b128 v[228:231], v169 offset:54272
	ds_read_b128 v[238:241], v169 offset:55296
	ds_read_b128 v[242:245], v169 offset:56320
	global_load_lds_dwordx4 v[200:201], off
	v_lshl_add_u64 v[200:201], v[246:247], 0, s[80:81]
	s_mov_b32 m0, s61
	s_addc_u32 s73, vcc_hi, 0
	global_load_lds_dwordx4 v[200:201], off
	v_lshl_add_u64 v[200:201], s[72:73], 0, v[0:1]
	s_mov_b32 m0, s66
	s_nop 0
	global_load_lds_dwordx4 v[200:201], off
	v_lshl_add_u64 v[200:201], s[72:73], 0, v[150:151]
	s_mov_b32 m0, s83
	s_nop 0
	global_load_lds_dwordx4 v[200:201], off
	v_lshl_add_u64 v[200:201], v[248:249], 0, s[80:81]
	s_mov_b32 m0, s62
	s_nop 0
	global_load_lds_dwordx4 v[200:201], off
	v_lshl_add_u64 v[200:201], v[250:251], 0, s[80:81]
	s_mov_b32 m0, s63
	s_nop 0
	global_load_lds_dwordx4 v[200:201], off
	s_waitcnt vmcnt(8)
	s_waitcnt lgkmcnt(0)
	s_barrier
	s_setprio 1
	s_waitcnt lgkmcnt(0)
	v_mfma_f32_16x16x32_bf16 v[78:81], v[156:159], v[208:211], v[78:81]
	v_mfma_f32_16x16x32_bf16 v[74:77], v[174:177], v[208:211], v[74:77]
	v_mfma_f32_16x16x32_bf16 v[66:69], v[156:159], v[216:219], v[66:69]
	v_mfma_f32_16x16x32_bf16 v[58:61], v[174:177], v[216:219], v[58:61]
	v_mfma_f32_16x16x32_bf16 v[46:49], v[156:159], v[224:227], v[46:49]
	v_mfma_f32_16x16x32_bf16 v[42:45], v[174:177], v[224:227], v[42:45]
	v_mfma_f32_16x16x32_bf16 v[30:33], v[156:159], v[238:241], v[30:33]
	v_mfma_f32_16x16x32_bf16 v[26:29], v[174:177], v[238:241], v[26:29]
	v_mfma_f32_16x16x32_bf16 v[78:81], v[170:173], v[212:215], v[78:81]
	v_mfma_f32_16x16x32_bf16 v[74:77], v[178:181], v[212:215], v[74:77]
	v_mfma_f32_16x16x32_bf16 v[66:69], v[170:173], v[220:223], v[66:69]
	v_mfma_f32_16x16x32_bf16 v[58:61], v[178:181], v[220:223], v[58:61]
	v_mfma_f32_16x16x32_bf16 v[46:49], v[170:173], v[228:231], v[46:49]
	v_mfma_f32_16x16x32_bf16 v[42:45], v[178:181], v[228:231], v[42:45]
	v_mfma_f32_16x16x32_bf16 v[30:33], v[170:173], v[242:245], v[30:33]
	v_mfma_f32_16x16x32_bf16 v[26:29], v[178:181], v[242:245], v[26:29]
	s_setprio 0
	s_setprio 1
	v_mfma_f32_16x16x32_bf16 v[70:73], v[182:185], v[208:211], v[70:73]
	v_mfma_f32_16x16x32_bf16 v[62:65], v[190:193], v[208:211], v[62:65]
	v_mfma_f32_16x16x32_bf16 v[54:57], v[182:185], v[216:219], v[54:57]
	v_mfma_f32_16x16x32_bf16 v[50:53], v[190:193], v[216:219], v[50:53]
	v_mfma_f32_16x16x32_bf16 v[38:41], v[182:185], v[224:227], v[38:41]
	v_mfma_f32_16x16x32_bf16 v[34:37], v[190:193], v[224:227], v[34:37]
	v_mfma_f32_16x16x32_bf16 v[22:25], v[182:185], v[238:241], v[22:25]
	v_mfma_f32_16x16x32_bf16 v[18:21], v[190:193], v[238:241], v[18:21]
	v_mfma_f32_16x16x32_bf16 v[70:73], v[186:189], v[212:215], v[70:73]
	v_mfma_f32_16x16x32_bf16 v[62:65], v[204:207], v[212:215], v[62:65]
	v_mfma_f32_16x16x32_bf16 v[54:57], v[186:189], v[220:223], v[54:57]
	v_mfma_f32_16x16x32_bf16 v[50:53], v[204:207], v[220:223], v[50:53]
	v_mfma_f32_16x16x32_bf16 v[38:41], v[186:189], v[228:231], v[38:41]
	v_mfma_f32_16x16x32_bf16 v[34:37], v[204:207], v[228:231], v[34:37]
	v_mfma_f32_16x16x32_bf16 v[22:25], v[186:189], v[242:245], v[22:25]
	v_mfma_f32_16x16x32_bf16 v[18:21], v[204:207], v[242:245], v[18:21]
	s_setprio 0
	s_barrier
	s_add_i32 s42, s42, 2
	s_add_u32 s44, s44, 0x100
	s_addc_u32 s45, s45, 0
	s_add_u32 s64, s64, 0x100
	s_addc_u32 s65, s65, 0
	s_branch .LBB0_596
.Lp2_zero:
	v_mov_b32_e32 v18, 0
	v_mov_b32_e32 v19, v18
	v_mov_b32_e32 v20, v18
	v_mov_b32_e32 v21, v18
	v_mov_b32_e32 v22, v18
	v_mov_b32_e32 v23, v18
	v_mov_b32_e32 v24, v18
	v_mov_b32_e32 v25, v18
	v_mov_b32_e32 v34, v18
	v_mov_b32_e32 v35, v18
	v_mov_b32_e32 v36, v18
	v_mov_b32_e32 v37, v18
	v_mov_b32_e32 v38, v18
	v_mov_b32_e32 v39, v18
	v_mov_b32_e32 v40, v18
	v_mov_b32_e32 v41, v18
	v_mov_b32_e32 v50, v18
	v_mov_b32_e32 v51, v18
	v_mov_b32_e32 v52, v18
	v_mov_b32_e32 v53, v18
	v_mov_b32_e32 v54, v18
	v_mov_b32_e32 v55, v18
	v_mov_b32_e32 v56, v18
	v_mov_b32_e32 v57, v18
	v_mov_b32_e32 v62, v18
	v_mov_b32_e32 v63, v18
	v_mov_b32_e32 v64, v18
	v_mov_b32_e32 v65, v18
	v_mov_b32_e32 v70, v18
	v_mov_b32_e32 v71, v18
	v_mov_b32_e32 v72, v18
	v_mov_b32_e32 v73, v18
	v_mov_b32_e32 v26, v18
	v_mov_b32_e32 v27, v18
	v_mov_b32_e32 v28, v18
	v_mov_b32_e32 v29, v18
	v_mov_b32_e32 v30, v18
	v_mov_b32_e32 v31, v18
	v_mov_b32_e32 v32, v18
	v_mov_b32_e32 v33, v18
	v_mov_b32_e32 v42, v18
	v_mov_b32_e32 v43, v18
	v_mov_b32_e32 v44, v18
	v_mov_b32_e32 v45, v18
	v_mov_b32_e32 v46, v18
	v_mov_b32_e32 v47, v18
	v_mov_b32_e32 v48, v18
	v_mov_b32_e32 v49, v18
	v_mov_b32_e32 v58, v18
	v_mov_b32_e32 v59, v18
	v_mov_b32_e32 v60, v18
	v_mov_b32_e32 v61, v18
	v_mov_b32_e32 v66, v18
	v_mov_b32_e32 v67, v18
	v_mov_b32_e32 v68, v18
	v_mov_b32_e32 v69, v18
	v_mov_b32_e32 v74, v18
	v_mov_b32_e32 v75, v18
	v_mov_b32_e32 v76, v18
	v_mov_b32_e32 v77, v18
	v_mov_b32_e32 v78, v18
	v_mov_b32_e32 v79, v18
	v_mov_b32_e32 v80, v18
	v_mov_b32_e32 v81, v18
	v_mov_b32_e32 v82, v18
	v_mov_b32_e32 v83, v18
	v_mov_b32_e32 v84, v18
	v_mov_b32_e32 v85, v18
	v_mov_b32_e32 v86, v18
	v_mov_b32_e32 v87, v18
	v_mov_b32_e32 v88, v18
	v_mov_b32_e32 v89, v18
	v_mov_b32_e32 v98, v18
	v_mov_b32_e32 v99, v18
	v_mov_b32_e32 v100, v18
	v_mov_b32_e32 v101, v18
	v_mov_b32_e32 v102, v18
	v_mov_b32_e32 v103, v18
	v_mov_b32_e32 v104, v18
	v_mov_b32_e32 v105, v18
	v_mov_b32_e32 v114, v18
	v_mov_b32_e32 v115, v18
	v_mov_b32_e32 v116, v18
	v_mov_b32_e32 v117, v18
	v_mov_b32_e32 v118, v18
	v_mov_b32_e32 v119, v18
	v_mov_b32_e32 v120, v18
	v_mov_b32_e32 v121, v18
	v_mov_b32_e32 v130, v18
	v_mov_b32_e32 v131, v18
	v_mov_b32_e32 v132, v18
	v_mov_b32_e32 v133, v18
	v_mov_b32_e32 v134, v18
	v_mov_b32_e32 v135, v18
	v_mov_b32_e32 v136, v18
	v_mov_b32_e32 v137, v18
	v_mov_b32_e32 v90, v18
	v_mov_b32_e32 v91, v18
	v_mov_b32_e32 v92, v18
	v_mov_b32_e32 v93, v18
	v_mov_b32_e32 v94, v18
	v_mov_b32_e32 v95, v18
	v_mov_b32_e32 v96, v18
	v_mov_b32_e32 v97, v18
	v_mov_b32_e32 v106, v18
	v_mov_b32_e32 v107, v18
	v_mov_b32_e32 v108, v18
	v_mov_b32_e32 v109, v18
	v_mov_b32_e32 v110, v18
	v_mov_b32_e32 v111, v18
	v_mov_b32_e32 v112, v18
	v_mov_b32_e32 v113, v18
	v_mov_b32_e32 v122, v18
	v_mov_b32_e32 v123, v18
	v_mov_b32_e32 v124, v18
	v_mov_b32_e32 v125, v18
	v_mov_b32_e32 v126, v18
	v_mov_b32_e32 v127, v18
	v_mov_b32_e32 v128, v18
	v_mov_b32_e32 v129, v18
	v_mov_b32_e32 v138, v18
	v_mov_b32_e32 v139, v18
	v_mov_b32_e32 v140, v18
	v_mov_b32_e32 v141, v18
	v_mov_b32_e32 v142, v18
	v_mov_b32_e32 v143, v18
	v_mov_b32_e32 v144, v18
	v_mov_b32_e32 v145, v18

.LBB0_618:
	s_waitcnt vmcnt(8)
	v_mov_b32_e32 v18, v3
	v_mov_b32_e32 v19, v4
	v_mov_b32_e32 v20, v2
	v_mov_b32_e32 v21, v5
	v_pk_add_f32 v[18:19], v[18:19], v[20:21]
	v_mov_b32_e32 v20, v7
	v_mov_b32_e32 v21, v8
	v_mov_b32_e32 v22, v6
	v_mov_b32_e32 v23, v9
	v_pk_add_f32 v[20:21], v[20:21], v[22:23]
	v_pk_add_f32 v[18:19], v[18:19], v[18:19] op_sel:[0,1] op_sel_hi:[1,0]
	v_pk_add_f32 v[20:21], v[20:21], v[20:21] op_sel:[0,1] op_sel_hi:[1,0]
	v_add_f32_e32 v22, v10, v11
	v_add_f32_e32 v24, v12, v13
	v_mov_b32_e32 v19, v14
	v_mov_b32_e32 v21, v15
	v_mov_b32_e32 v23, v16
	v_mov_b32_e32 v25, v17
	v_pk_add_f32 v[18:19], v[18:19], v[20:21]
	v_pk_add_f32 v[20:21], v[22:23], v[24:25]
	s_xor_b32 s1, s1, 0x400
	v_pk_add_f32 v[18:19], v[18:19], v[20:21]
	s_nop 0
	v_add_f32_e32 v18, v18, v19
	v_fmamk_f32 v18, v18, 0x3a800000, v234
	v_mul_f32_e32 v19, 0x4b800000, v18
	v_cmp_gt_f32_e32 vcc, s33, v18
	s_nop 1
	v_cndmask_b32_e32 v18, v18, v19, vcc
	v_rsq_f32_e32 v18, v18
	s_nop 0
	v_mul_f32_e32 v19, 0x45800000, v18
	v_cndmask_b32_e32 v18, v18, v19, vcc
	v_add_u32_e32 v19, s1, v163
	ds_write_b32 v19, v18
	s_or_b64 exec, exec, s[76:77]
	s_andn2_b64 vcc, exec, s[38:39]
	s_mov_b64 s[38:39], -1
	s_cbranch_vccnz .LBB0_592
	s_branch .LBB0_622
